# plus: lane-constant tile coordinates cached in a spare VGPR across units instead of ~38 VALU per unit
# speedup vs baseline: 1.0261x; 1.0013x over previous
; template <class Epi, class Sched>
; __device__ __forceinline__ void gemm_phase(LAS unsigned char* lds, const int tid, const Sched& S, const Epi& E) {
;     ...
;         { int t3 = tid; asm volatile("" : "+v"(t3));
;           int R0n, C0n; stage_rc(t3 * 16, R0n, C0n); const int RBn = Epi::PERM ? ((R0n & ~31) + perm32(R0n & 31)) : R0n;
;           noffA = (unsigned)R0n * (unsigned)nlda + (unsigned)C0n * 2u; noffB = (unsigned)RBn * (unsigned)nldb + (unsigned)C0n * 2u; }
;         const int nqA = 64 * nlda, nqB = 64 * nldb, nhA = 128 * nlda, nhB = 128 * nldb;
;         const int nt = cur.nt;
;         for (int t = 0; t < nt; t += 2) {
;     ...
; #pragma unroll
;         for (int a = 0; a < 2; ++a)
; #pragma unroll
;             for (int b = 0; b < 2; ++b)
; #pragma unroll
;                 for (int m = 0; m < 4; ++m)
; #pragma unroll
;                     for (int n = 0; n < 2; ++n) acc[a][b][m][n] = (f32x4){0.f, 0.f, 0.f, 0.f};
.LBB0_171:
	s_cmp_lt_u32 s89, 2
	s_cbranch_scc0 .Lrc_fast
	v_mov_b32_e32 v0, v183
	s_and_b64 s[2:3], s[60:61], exec
	v_ashrrev_i32_e32 v3, 31, v0
	v_lshrrev_b32_e32 v3, 26, v3
	v_lshlrev_b32_e32 v2, 4, v0
	v_add_u32_e32 v3, v0, v3
	v_bfe_i32 v0, v0, 27, 1
	v_lshrrev_b32_e32 v0, 22, v0
	v_add_u32_e32 v0, v2, v0
	v_and_b32_e32 v0, 0xfffffc00, v0
	v_sub_u32_e32 v0, v2, v0
	v_lshrrev_b32_e32 v2, 4, v0
	v_bitop3_b32 v0, v2, v0, 32 bitop3:0x6c
	v_ashrrev_i32_e32 v4, 31, v0
	v_ashrrev_i32_e32 v3, 6, v3
	v_lshrrev_b32_e32 v4, 26, v4
	v_lshlrev_b32_e32 v2, 3, v3
	v_add_u32_e32 v4, v0, v4
	v_and_b32_e32 v2, -16, v2
	v_ashrrev_i32_e32 v5, 6, v4
	v_and_b32_e32 v4, 0xc0, v4
	v_add_u32_e32 v2, v5, v2
	v_sub_u32_e32 v0, v0, v4
	v_lshlrev_b32_e32 v3, 5, v3
	v_ashrrev_i16_sdwa v0, v165, sext(v0) dst_sel:DWORD dst_unused:UNUSED_PAD src0_sel:DWORD src1_sel:BYTE_0
	v_lshlrev_b32_e32 v4, 1, v2
	v_lshrrev_b32_e32 v6, 2, v2
	v_and_b32_e32 v5, 3, v5
	s_movk_i32 s2, 0xffe0
	v_and_b32_e32 v3, 32, v3
	v_bfe_i32 v0, v0, 0, 16
	v_and_b32_e32 v4, 24, v4
	v_and_b32_e32 v6, 4, v6
	v_and_or_b32 v5, v2, s2, v5
	s_cselect_b32 s6, s90, s17
	s_cselect_b32 s7, s92, s16
	v_or3_b32 v4, v5, v6, v4
	v_add_lshl_u32 v0, v3, v0, 1
	v_lshl_or_b32 v243, v4, 8, v2
	v_lshl_or_b32 v243, v0, 16, v243
	s_branch .Lrc_join
.Lrc_fast:
	s_and_b64 s[2:3], s[60:61], exec
	s_cselect_b32 s6, s90, s17
	s_cselect_b32 s7, s92, s16
	v_and_b32_e32 v2, 0xff, v243
	v_bfe_u32 v4, v243, 8, 8
	v_lshrrev_b32_e32 v0, 16, v243
.Lrc_join:
	v_mad_u64_u32 v[130:131], s[2:3], v2, s6, v[0:1]
	v_mad_u64_u32 v[132:133], s[2:3], v4, s7, v[0:1]
	s_lshl_b32 s2, s6, 6
	s_lshl_b32 s18, s7, 6
	s_lshl_b32 s84, s6, 7
	s_lshl_b32 s69, s7, 7
	s_cmp_lt_i32 s37, 1
	s_cbranch_scc1 .LBB0_178
	s_and_b64 s[6:7], s[60:61], exec
	s_cselect_b32 s82, s75, s41
	s_cselect_b32 s48, s74, s40
	s_cselect_b32 s15, s87, s43
	s_cselect_b32 s14, s86, s42
	s_add_i32 s49, s37, -2
	s_ashr_i32 s97, s96, 31
	s_mov_b32 s4, s68
	s_add_u32 s68, s40, s96
	s_addc_u32 s16, s41, s97
	v_mov_b32_e32 v135, v1
	s_ashr_i32 s67, s66, 31
	v_mov_b32_e32 v131, v1
	s_ashr_i32 s3, s2, 31
	s_ashr_i32 s85, s84, 31
	s_mov_b32 s17, 0
	s_cmp_lt_u32 s89, 2
	s_cbranch_scc0 .Lk0_dispatch
	v_mov_b32_e32 v2, 0
	v_mov_b32_e32 v3, v2
	v_mov_b32_e32 v4, v2
	v_mov_b32_e32 v5, v2
	v_mov_b32_e32 v6, v2
	v_mov_b32_e32 v7, v2
	v_mov_b32_e32 v8, v2
	v_mov_b32_e32 v9, v2
	v_mov_b32_e32 v18, v2
	v_mov_b32_e32 v19, v2
	v_mov_b32_e32 v20, v2
	v_mov_b32_e32 v21, v2
	v_mov_b32_e32 v22, v2
	v_mov_b32_e32 v23, v2
	v_mov_b32_e32 v24, v2
	v_mov_b32_e32 v25, v2
	v_mov_b32_e32 v34, v2
	v_mov_b32_e32 v35, v2
	v_mov_b32_e32 v36, v2
	v_mov_b32_e32 v37, v2
	v_mov_b32_e32 v38, v2
	v_mov_b32_e32 v39, v2
	v_mov_b32_e32 v40, v2
	v_mov_b32_e32 v41, v2
	v_mov_b32_e32 v50, v2
	v_mov_b32_e32 v51, v2
	v_mov_b32_e32 v52, v2
	v_mov_b32_e32 v53, v2
	v_mov_b32_e32 v54, v2
	v_mov_b32_e32 v55, v2
	v_mov_b32_e32 v56, v2
	v_mov_b32_e32 v57, v2
	v_mov_b32_e32 v10, v2
	v_mov_b32_e32 v11, v2
	v_mov_b32_e32 v12, v2
	v_mov_b32_e32 v13, v2
	v_mov_b32_e32 v14, v2
	v_mov_b32_e32 v15, v2
	v_mov_b32_e32 v16, v2
	v_mov_b32_e32 v17, v2
	v_mov_b32_e32 v26, v2
	v_mov_b32_e32 v27, v2
	v_mov_b32_e32 v28, v2
	v_mov_b32_e32 v29, v2
	v_mov_b32_e32 v30, v2
	v_mov_b32_e32 v31, v2
	v_mov_b32_e32 v32, v2
	v_mov_b32_e32 v33, v2
	v_mov_b32_e32 v42, v2
	v_mov_b32_e32 v43, v2
	v_mov_b32_e32 v44, v2
	v_mov_b32_e32 v45, v2
	v_mov_b32_e32 v46, v2
	v_mov_b32_e32 v47, v2
	v_mov_b32_e32 v48, v2
	v_mov_b32_e32 v49, v2
	v_mov_b32_e32 v58, v2
	v_mov_b32_e32 v59, v2
	v_mov_b32_e32 v60, v2
	v_mov_b32_e32 v61, v2
	v_mov_b32_e32 v62, v2
	v_mov_b32_e32 v63, v2
	v_mov_b32_e32 v64, v2
	v_mov_b32_e32 v65, v2
	v_mov_b32_e32 v66, v2
	v_mov_b32_e32 v67, v2
	v_mov_b32_e32 v68, v2
	v_mov_b32_e32 v69, v2
	v_mov_b32_e32 v70, v2
	v_mov_b32_e32 v71, v2
	v_mov_b32_e32 v72, v2
	v_mov_b32_e32 v73, v2
	v_mov_b32_e32 v82, v2
	v_mov_b32_e32 v83, v2
	v_mov_b32_e32 v84, v2
	v_mov_b32_e32 v85, v2
	v_mov_b32_e32 v86, v2
	v_mov_b32_e32 v87, v2
	v_mov_b32_e32 v88, v2
	v_mov_b32_e32 v89, v2
	v_mov_b32_e32 v98, v2
	v_mov_b32_e32 v99, v2
	v_mov_b32_e32 v100, v2
	v_mov_b32_e32 v101, v2
	v_mov_b32_e32 v102, v2
	v_mov_b32_e32 v103, v2
	v_mov_b32_e32 v104, v2
	v_mov_b32_e32 v105, v2
	v_mov_b32_e32 v114, v2
	v_mov_b32_e32 v115, v2
	v_mov_b32_e32 v116, v2
	v_mov_b32_e32 v117, v2
	v_mov_b32_e32 v118, v2
	v_mov_b32_e32 v119, v2
	v_mov_b32_e32 v120, v2
	v_mov_b32_e32 v121, v2
	v_mov_b32_e32 v74, v2
	v_mov_b32_e32 v75, v2
	v_mov_b32_e32 v76, v2
	v_mov_b32_e32 v77, v2
	v_mov_b32_e32 v78, v2
	v_mov_b32_e32 v79, v2
	v_mov_b32_e32 v80, v2
	v_mov_b32_e32 v81, v2
	v_mov_b32_e32 v90, v2
	v_mov_b32_e32 v91, v2
	v_mov_b32_e32 v92, v2
	v_mov_b32_e32 v93, v2
	v_mov_b32_e32 v94, v2
	v_mov_b32_e32 v95, v2
	v_mov_b32_e32 v96, v2
	v_mov_b32_e32 v97, v2
	v_mov_b32_e32 v106, v2
	v_mov_b32_e32 v107, v2
	v_mov_b32_e32 v108, v2
	v_mov_b32_e32 v109, v2
	v_mov_b32_e32 v110, v2
	v_mov_b32_e32 v111, v2
	v_mov_b32_e32 v112, v2
	v_mov_b32_e32 v113, v2
	v_mov_b32_e32 v122, v2
	v_mov_b32_e32 v123, v2
	v_mov_b32_e32 v124, v2
	v_mov_b32_e32 v125, v2
	v_mov_b32_e32 v126, v2
	v_mov_b32_e32 v127, v2
	v_mov_b32_e32 v128, v2
	v_mov_b32_e32 v129, v2
	s_branch .LBB0_173
